# conv phase rewritten by hand: 4 adjacent positions per wave-task from one 3x6 window, shared bf16 unpacks, scalar boundary flags, DPP 16-lane butterfly; same arithmetic order
# speedup vs baseline: 1.0425x; 1.0236x over previous
; template <int MODE>
; __device__ __forceinline__ void conv_pass(const Params& p, int l, int gw, int nw, int lane) {
;     ...
;     const int hp = gw & 3, sub = lane >> 5, part = (lane >> 4) & 1;
;     chn = part * 1024 + (hp * 2 + sub) * 128 + c8 * 8; ntask = TG * 4; tshift = 2; isq = (part == 0);
;   } else {
;     const int hq = gw & 1, sub = lane >> 4;
;     chn = 2048 + (hq * 4 + sub) * 128 + c8 * 8; ntask = TG * 2; tshift = 1;
;   }
;   float4 wa[9], wb[9];
;   {
;     const float* cwb = p.gdn_conv + (long)l * 9 * 3072 + chn;
; #pragma unroll
;     for (int k = 0; k < 9; ++k) { wa[k] = *(const float4*)(cwb + k * 3072); wb[k] = *(const float4*)(cwb + k * 3072 + 4); }
;   }
;   uint4 nx0, nx1, nx2, nx3, nx4, nx5, nx6, nx7, nx8;
.LBB0_317:
	v_readlane_b32 s38, v241, 2
	v_lshrrev_b32_e32 v0, 6, v156
	s_lshr_b32 s54, s38, 2
	v_readlane_b32 s10, v241, 59
	v_readfirstlane_b32 s51, v0
	v_readlane_b32 s12, v242, 0
	v_readlane_b32 s13, v242, 1
	s_nop 0
	s_load_dwordx2 s[42:43], s[12:13], 0x50
	s_mul_i32 s10, s10, 0x1b000
	s_waitcnt lgkmcnt(0)
	s_add_u32 s42, s42, s10
	s_addc_u32 s43, s43, 0
	v_and_b32_e32 v0, 63, v156
	v_lshrrev_b32_e32 v146, 5, v0
	v_bfe_u32 v147, v0, 4, 1
	v_and_b32_e32 v0, 15, v0
	s_lshl_b32 s55, s51, 1
	v_add_u32_e32 v146, s55, v146
	v_lshlrev_b32_e32 v146, 7, v146
	v_lshl_add_u32 v146, v147, 10, v146
	v_lshl_add_u32 v146, v0, 3, v146
	v_lshlrev_b32_e32 v150, 1, v146
	v_lshlrev_b32_e32 v153, 2, v146
	v_cmp_eq_u32_e32 vcc, 0, v147
	v_mov_b32_e32 v151, 1.0
	v_mov_b32_e32 v0, 0x3db504f3
	s_nop 1
	v_cndmask_b32_e32 v151, v151, v0, vcc
	s_mov_b64 s[40:41], s[42:43]
	global_load_dwordx4 v[2:5], v153, s[40:41]
	global_load_dwordx4 v[6:9], v153, s[40:41] offset:16
	s_add_u32 s40, s40, 0x3000
	s_addc_u32 s41, s41, 0
	global_load_dwordx4 v[10:13], v153, s[40:41]
	global_load_dwordx4 v[14:17], v153, s[40:41] offset:16
	s_add_u32 s40, s40, 0x3000
	s_addc_u32 s41, s41, 0
	global_load_dwordx4 v[18:21], v153, s[40:41]
	global_load_dwordx4 v[22:25], v153, s[40:41] offset:16
	s_add_u32 s40, s40, 0x3000
	s_addc_u32 s41, s41, 0
	global_load_dwordx4 v[26:29], v153, s[40:41]
	global_load_dwordx4 v[30:33], v153, s[40:41] offset:16
	s_add_u32 s40, s40, 0x3000
	s_addc_u32 s41, s41, 0
	global_load_dwordx4 v[34:37], v153, s[40:41]
	global_load_dwordx4 v[38:41], v153, s[40:41] offset:16
	s_add_u32 s40, s40, 0x3000
	s_addc_u32 s41, s41, 0
	global_load_dwordx4 v[42:45], v153, s[40:41]
	global_load_dwordx4 v[46:49], v153, s[40:41] offset:16
	s_add_u32 s40, s40, 0x3000
	s_addc_u32 s41, s41, 0
	global_load_dwordx4 v[50:53], v153, s[40:41]
	global_load_dwordx4 v[54:57], v153, s[40:41] offset:16
	s_add_u32 s40, s40, 0x3000
	s_addc_u32 s41, s41, 0
	global_load_dwordx4 v[58:61], v153, s[40:41]
	global_load_dwordx4 v[62:65], v153, s[40:41] offset:16
	s_add_u32 s40, s40, 0x3000
	s_addc_u32 s41, s41, 0
	global_load_dwordx4 v[66:69], v153, s[40:41]
	global_load_dwordx4 v[70:73], v153, s[40:41] offset:16
	s_mov_b32 s48, s54
	s_movk_i32 s49, 0x200
	s_cmpk_lt_u32 s48, 0x900
	s_cbranch_scc0 .Lcv0_done
	s_mul_hi_u32 s10, s48, 0x71c71d
	s_mul_i32 s12, s10, 0x240
	s_sub_i32 s12, s48, s12
	s_sub_i32 s13, s12, 64
	s_and_b32 s55, s13, 15
	s_cmpk_lt_u32 s12, 64
	s_cselect_b32 s55, s12, s55
	s_cselect_b32 s10, 63, 15
	s_cselect_b32 s39, 0, 1
	s_cmp_gt_u32 s55, 0
	s_cselect_b32 s50, 4, 0
	s_cmp_lt_u32 s55, s10
	s_cselect_b32 s38, 8, 0
	s_or_b32 s50, s50, s38
	s_cmp_ge_i32 s13, 16
	s_cselect_b32 s38, 1, 0
	s_and_b32 s38, s38, s39
	s_or_b32 s50, s50, s38
	s_cmpk_lt_i32 s13, 0x1f0
	s_cselect_b32 s38, 2, 0
	s_lshl_b32 s39, s39, 1
	s_and_b32 s38, s38, s39
	s_or_b32 s50, s50, s38
	s_mul_i32 s38, s48, 0x6000
	s_add_u32 s46, s88, s38
	s_addc_u32 s47, s89, 0
	s_lshl_b32 s38, s48, 17
	s_add_u32 s52, s86, s38
	s_addc_u32 s53, s87, 0
	s_add_u32 s52, s52, 0x2800
	s_addc_u32 s53, s53, 0
	s_bitcmp1_b32 s50, 0
	s_cbranch_scc0 .Lcv0p_zr0
	s_sub_u32 s38, s46, 0x61800
	s_subb_u32 s39, s47, 0
	s_bitcmp1_b32 s50, 2
	s_cbranch_scc0 .Lcv0p_z00
	global_load_dwordx4 v[74:77], v150, s[38:39]
	s_branch .Lcv0p_d00
.Lcv0p_z00:
	v_mov_b32_e32 v74, 0
	v_mov_b32_e32 v75, 0
	v_mov_b32_e32 v76, 0
	v_mov_b32_e32 v77, 0
.Lcv0p_d00:
	s_add_u32 s38, s38, 0x1800
	s_addc_u32 s39, s39, 0
	global_load_dwordx4 v[78:81], v150, s[38:39]
	s_add_u32 s38, s38, 0x1800
	s_addc_u32 s39, s39, 0
	global_load_dwordx4 v[82:85], v150, s[38:39]
	s_add_u32 s38, s38, 0x1800
	s_addc_u32 s39, s39, 0
	global_load_dwordx4 v[86:89], v150, s[38:39]
	s_add_u32 s38, s38, 0x1800
	s_addc_u32 s39, s39, 0
	global_load_dwordx4 v[90:93], v150, s[38:39]
	s_add_u32 s38, s38, 0x1800
	s_addc_u32 s39, s39, 0
	s_bitcmp1_b32 s50, 3
	s_cbranch_scc0 .Lcv0p_z05
	global_load_dwordx4 v[94:97], v150, s[38:39]
	s_branch .Lcv0p_d05
.Lcv0p_z05:
	v_mov_b32_e32 v94, 0
	v_mov_b32_e32 v95, 0
	v_mov_b32_e32 v96, 0
	v_mov_b32_e32 v97, 0
.Lcv0p_d05:
	s_branch .Lcv0p_dr0
.Lcv0p_zr0:
	v_mov_b32_e32 v74, 0
	v_mov_b32_e32 v75, 0
	v_mov_b32_e32 v76, 0
	v_mov_b32_e32 v77, 0
	v_mov_b32_e32 v78, 0
	v_mov_b32_e32 v79, 0
	v_mov_b32_e32 v80, 0
	v_mov_b32_e32 v81, 0
	v_mov_b32_e32 v82, 0
	v_mov_b32_e32 v83, 0
	v_mov_b32_e32 v84, 0
	v_mov_b32_e32 v85, 0
	v_mov_b32_e32 v86, 0
	v_mov_b32_e32 v87, 0
	v_mov_b32_e32 v88, 0
	v_mov_b32_e32 v89, 0
	v_mov_b32_e32 v90, 0
	v_mov_b32_e32 v91, 0
	v_mov_b32_e32 v92, 0
	v_mov_b32_e32 v93, 0
	v_mov_b32_e32 v94, 0
	v_mov_b32_e32 v95, 0
	v_mov_b32_e32 v96, 0
	v_mov_b32_e32 v97, 0
.Lcv0p_dr0:
	s_sub_u32 s38, s46, 0x1800
	s_subb_u32 s39, s47, 0
	s_bitcmp1_b32 s50, 2
	s_cbranch_scc0 .Lcv0p_z10
	global_load_dwordx4 v[98:101], v150, s[38:39]
	s_branch .Lcv0p_d10
.Lcv0p_z10:
	v_mov_b32_e32 v98, 0
	v_mov_b32_e32 v99, 0
	v_mov_b32_e32 v100, 0
	v_mov_b32_e32 v101, 0
.Lcv0p_d10:
	s_add_u32 s38, s38, 0x1800
	s_addc_u32 s39, s39, 0
	global_load_dwordx4 v[102:105], v150, s[38:39]
	s_add_u32 s38, s38, 0x1800
	s_addc_u32 s39, s39, 0
	global_load_dwordx4 v[106:109], v150, s[38:39]
	s_add_u32 s38, s38, 0x1800
	s_addc_u32 s39, s39, 0
	global_load_dwordx4 v[110:113], v150, s[38:39]
	s_add_u32 s38, s38, 0x1800
	s_addc_u32 s39, s39, 0
	global_load_dwordx4 v[114:117], v150, s[38:39]
	s_add_u32 s38, s38, 0x1800
	s_addc_u32 s39, s39, 0
	s_bitcmp1_b32 s50, 3
	s_cbranch_scc0 .Lcv0p_z15
	global_load_dwordx4 v[118:121], v150, s[38:39]
	s_branch .Lcv0p_d15
.Lcv0p_z15:
	v_mov_b32_e32 v118, 0
	v_mov_b32_e32 v119, 0
	v_mov_b32_e32 v120, 0
	v_mov_b32_e32 v121, 0
.Lcv0p_d15:
	s_bitcmp1_b32 s50, 1
	s_cbranch_scc0 .Lcv0p_zr2
	s_add_u32 s38, s46, 0x5e800
	s_addc_u32 s39, s47, 0
	s_bitcmp1_b32 s50, 2
	s_cbranch_scc0 .Lcv0p_z20
	global_load_dwordx4 v[122:125], v150, s[38:39]
	s_branch .Lcv0p_d20
.Lcv0p_z20:
	v_mov_b32_e32 v122, 0
	v_mov_b32_e32 v123, 0
	v_mov_b32_e32 v124, 0
	v_mov_b32_e32 v125, 0
.Lcv0p_d20:
	s_add_u32 s38, s38, 0x1800
	s_addc_u32 s39, s39, 0
	global_load_dwordx4 v[126:129], v150, s[38:39]
	s_add_u32 s38, s38, 0x1800
	s_addc_u32 s39, s39, 0
	global_load_dwordx4 v[130:133], v150, s[38:39]
	s_add_u32 s38, s38, 0x1800
	s_addc_u32 s39, s39, 0
	global_load_dwordx4 v[134:137], v150, s[38:39]
	s_add_u32 s38, s38, 0x1800
	s_addc_u32 s39, s39, 0
	global_load_dwordx4 v[138:141], v150, s[38:39]
	s_add_u32 s38, s38, 0x1800
	s_addc_u32 s39, s39, 0
	s_bitcmp1_b32 s50, 3
	s_cbranch_scc0 .Lcv0p_z25
	global_load_dwordx4 v[142:145], v150, s[38:39]
	s_branch .Lcv0p_d25
.Lcv0p_z25:
	v_mov_b32_e32 v142, 0
	v_mov_b32_e32 v143, 0
	v_mov_b32_e32 v144, 0
	v_mov_b32_e32 v145, 0

; template <int MODE>
; __device__ __forceinline__ void conv_pass(const Params& p, int l, int gw, int nw, int lane) {
;     ...
;   CONV_LOAD(gw)
;   for (int task = gw; task < ntask; task += nw) {
;     const uint4 c0 = nx0, c1 = nx1, c2 = nx2, c3 = nx3, c4 = nx4, c5 = nx5, c6 = nx6, c7 = nx7, c8r = nx8;
;     CONV_LOAD(task + nw)
;     int row = task >> tshift;
;     float val[8];
; #pragma unroll
;     for (int e = 0; e < 8; ++e) val[e] = 0.f;
;     CONV_TAP(c0, 0) CONV_TAP(c1, 1) CONV_TAP(c2, 2) CONV_TAP(c3, 3) CONV_TAP(c4, 4)
;     CONV_TAP(c5, 5) CONV_TAP(c6, 6) CONV_TAP(c7, 7) CONV_TAP(c8r, 8)
.Lcv0p_zr2:
	v_mov_b32_e32 v122, 0
	v_mov_b32_e32 v123, 0
	v_mov_b32_e32 v124, 0
	v_mov_b32_e32 v125, 0
	v_mov_b32_e32 v126, 0
	v_mov_b32_e32 v127, 0
	v_mov_b32_e32 v128, 0
	v_mov_b32_e32 v129, 0
	v_mov_b32_e32 v130, 0
	v_mov_b32_e32 v131, 0
	v_mov_b32_e32 v132, 0
	v_mov_b32_e32 v133, 0
	v_mov_b32_e32 v134, 0
	v_mov_b32_e32 v135, 0
	v_mov_b32_e32 v136, 0
	v_mov_b32_e32 v137, 0
	v_mov_b32_e32 v138, 0
	v_mov_b32_e32 v139, 0
	v_mov_b32_e32 v140, 0
	v_mov_b32_e32 v141, 0
	v_mov_b32_e32 v142, 0
	v_mov_b32_e32 v143, 0
	v_mov_b32_e32 v144, 0
	v_mov_b32_e32 v145, 0
.Lcv0p_dr2:
	s_waitcnt vmcnt(0)
	s_branch .Lcv0_compute
.Lcv0_loop:
	s_waitcnt vmcnt(4)
.Lcv0_compute:
	s_mov_b64 s[44:45], s[52:53]
	v_mov_b32_e32 v200, 0
	v_mov_b32_e32 v201, 0
	v_mov_b32_e32 v202, 0
	v_mov_b32_e32 v203, 0
	v_mov_b32_e32 v204, 0
	v_mov_b32_e32 v205, 0
	v_mov_b32_e32 v206, 0
	v_mov_b32_e32 v207, 0
	v_mov_b32_e32 v208, 0
	v_mov_b32_e32 v209, 0
	v_mov_b32_e32 v210, 0
	v_mov_b32_e32 v211, 0
	v_mov_b32_e32 v212, 0
	v_mov_b32_e32 v213, 0
	v_mov_b32_e32 v214, 0
	v_mov_b32_e32 v215, 0
	v_mov_b32_e32 v216, 0
	v_mov_b32_e32 v217, 0
	v_mov_b32_e32 v218, 0
	v_mov_b32_e32 v219, 0
	v_mov_b32_e32 v220, 0
	v_mov_b32_e32 v221, 0
	v_mov_b32_e32 v222, 0
	v_mov_b32_e32 v223, 0
	v_mov_b32_e32 v224, 0
	v_mov_b32_e32 v225, 0
	v_mov_b32_e32 v226, 0
	v_mov_b32_e32 v227, 0
	v_mov_b32_e32 v228, 0
	v_mov_b32_e32 v229, 0
	v_mov_b32_e32 v230, 0
	v_mov_b32_e32 v231, 0
	v_lshlrev_b32_e32 v232, 16, v74
	v_and_b32_e32 v233, 0xffff0000, v74
	v_lshlrev_b32_e32 v234, 16, v75
	v_and_b32_e32 v235, 0xffff0000, v75
	v_lshlrev_b32_e32 v236, 16, v76
	v_and_b32_e32 v237, 0xffff0000, v76
	v_lshlrev_b32_e32 v238, 16, v77
	v_and_b32_e32 v239, 0xffff0000, v77
	v_pk_fma_f32 v[200:201], v[2:3], v[232:233], v[200:201]
	v_pk_fma_f32 v[202:203], v[4:5], v[234:235], v[202:203]
	v_pk_fma_f32 v[204:205], v[6:7], v[236:237], v[204:205]
	v_pk_fma_f32 v[206:207], v[8:9], v[238:239], v[206:207]
	v_lshlrev_b32_e32 v232, 16, v78
	v_and_b32_e32 v233, 0xffff0000, v78
	v_lshlrev_b32_e32 v234, 16, v79
	v_and_b32_e32 v235, 0xffff0000, v79
	v_lshlrev_b32_e32 v236, 16, v80
	v_and_b32_e32 v237, 0xffff0000, v80
	v_lshlrev_b32_e32 v238, 16, v81
	v_and_b32_e32 v239, 0xffff0000, v81
	v_pk_fma_f32 v[200:201], v[10:11], v[232:233], v[200:201]
	v_pk_fma_f32 v[202:203], v[12:13], v[234:235], v[202:203]
	v_pk_fma_f32 v[204:205], v[14:15], v[236:237], v[204:205]
	v_pk_fma_f32 v[206:207], v[16:17], v[238:239], v[206:207]
	v_pk_fma_f32 v[208:209], v[2:3], v[232:233], v[208:209]
	v_pk_fma_f32 v[210:211], v[4:5], v[234:235], v[210:211]
	v_pk_fma_f32 v[212:213], v[6:7], v[236:237], v[212:213]
	v_pk_fma_f32 v[214:215], v[8:9], v[238:239], v[214:215]
	v_lshlrev_b32_e32 v232, 16, v82
	v_and_b32_e32 v233, 0xffff0000, v82
	v_lshlrev_b32_e32 v234, 16, v83
	v_and_b32_e32 v235, 0xffff0000, v83
	v_lshlrev_b32_e32 v236, 16, v84
	v_and_b32_e32 v237, 0xffff0000, v84
	v_lshlrev_b32_e32 v238, 16, v85
	v_and_b32_e32 v239, 0xffff0000, v85
	v_pk_fma_f32 v[200:201], v[18:19], v[232:233], v[200:201]
	v_pk_fma_f32 v[202:203], v[20:21], v[234:235], v[202:203]
	v_pk_fma_f32 v[204:205], v[22:23], v[236:237], v[204:205]
	v_pk_fma_f32 v[206:207], v[24:25], v[238:239], v[206:207]
	v_pk_fma_f32 v[208:209], v[10:11], v[232:233], v[208:209]
	v_pk_fma_f32 v[210:211], v[12:13], v[234:235], v[210:211]
	v_pk_fma_f32 v[212:213], v[14:15], v[236:237], v[212:213]
	v_pk_fma_f32 v[214:215], v[16:17], v[238:239], v[214:215]
	v_pk_fma_f32 v[216:217], v[2:3], v[232:233], v[216:217]
	v_pk_fma_f32 v[218:219], v[4:5], v[234:235], v[218:219]
	v_pk_fma_f32 v[220:221], v[6:7], v[236:237], v[220:221]
	v_pk_fma_f32 v[222:223], v[8:9], v[238:239], v[222:223]
	v_lshlrev_b32_e32 v232, 16, v86
	v_and_b32_e32 v233, 0xffff0000, v86
	v_lshlrev_b32_e32 v234, 16, v87
	v_and_b32_e32 v235, 0xffff0000, v87
	v_lshlrev_b32_e32 v236, 16, v88
	v_and_b32_e32 v237, 0xffff0000, v88
	v_lshlrev_b32_e32 v238, 16, v89
	v_and_b32_e32 v239, 0xffff0000, v89
	v_pk_fma_f32 v[208:209], v[18:19], v[232:233], v[208:209]
	v_pk_fma_f32 v[210:211], v[20:21], v[234:235], v[210:211]
	v_pk_fma_f32 v[212:213], v[22:23], v[236:237], v[212:213]
	v_pk_fma_f32 v[214:215], v[24:25], v[238:239], v[214:215]
	v_pk_fma_f32 v[216:217], v[10:11], v[232:233], v[216:217]
	v_pk_fma_f32 v[218:219], v[12:13], v[234:235], v[218:219]
	v_pk_fma_f32 v[220:221], v[14:15], v[236:237], v[220:221]
	v_pk_fma_f32 v[222:223], v[16:17], v[238:239], v[222:223]
	v_pk_fma_f32 v[224:225], v[2:3], v[232:233], v[224:225]
	v_pk_fma_f32 v[226:227], v[4:5], v[234:235], v[226:227]
	v_pk_fma_f32 v[228:229], v[6:7], v[236:237], v[228:229]
	v_pk_fma_f32 v[230:231], v[8:9], v[238:239], v[230:231]
	v_lshlrev_b32_e32 v232, 16, v90
	v_and_b32_e32 v233, 0xffff0000, v90
	v_lshlrev_b32_e32 v234, 16, v91
	v_and_b32_e32 v235, 0xffff0000, v91
	v_lshlrev_b32_e32 v236, 16, v92
	v_and_b32_e32 v237, 0xffff0000, v92
	v_lshlrev_b32_e32 v238, 16, v93
	v_and_b32_e32 v239, 0xffff0000, v93
	v_pk_fma_f32 v[216:217], v[18:19], v[232:233], v[216:217]
	v_pk_fma_f32 v[218:219], v[20:21], v[234:235], v[218:219]
	v_pk_fma_f32 v[220:221], v[22:23], v[236:237], v[220:221]
	v_pk_fma_f32 v[222:223], v[24:25], v[238:239], v[222:223]
	v_pk_fma_f32 v[224:225], v[10:11], v[232:233], v[224:225]
	v_pk_fma_f32 v[226:227], v[12:13], v[234:235], v[226:227]
	v_pk_fma_f32 v[228:229], v[14:15], v[236:237], v[228:229]
	v_pk_fma_f32 v[230:231], v[16:17], v[238:239], v[230:231]
	v_lshlrev_b32_e32 v232, 16, v94
	v_and_b32_e32 v233, 0xffff0000, v94
	v_lshlrev_b32_e32 v234, 16, v95
	v_and_b32_e32 v235, 0xffff0000, v95
	v_lshlrev_b32_e32 v236, 16, v96
	v_and_b32_e32 v237, 0xffff0000, v96
	v_lshlrev_b32_e32 v238, 16, v97
; template <int MODE>
; __device__ __forceinline__ void conv_pass(const Params& p, int l, int gw, int nw, int lane) {
;     ...
;   CONV_LOAD(gw)
;   for (int task = gw; task < ntask; task += nw) {
;     const uint4 c0 = nx0, c1 = nx1, c2 = nx2, c3 = nx3, c4 = nx4, c5 = nx5, c6 = nx6, c7 = nx7, c8r = nx8;
;     CONV_LOAD(task + nw)
;     int row = task >> tshift;
;     float val[8];
; #pragma unroll
;     for (int e = 0; e < 8; ++e) val[e] = 0.f;
;     CONV_TAP(c0, 0) CONV_TAP(c1, 1) CONV_TAP(c2, 2) CONV_TAP(c3, 3) CONV_TAP(c4, 4)
;     CONV_TAP(c5, 5) CONV_TAP(c6, 6) CONV_TAP(c7, 7) CONV_TAP(c8r, 8)
	v_and_b32_e32 v239, 0xffff0000, v97
	v_pk_fma_f32 v[224:225], v[18:19], v[232:233], v[224:225]
	v_pk_fma_f32 v[226:227], v[20:21], v[234:235], v[226:227]
	v_pk_fma_f32 v[228:229], v[22:23], v[236:237], v[228:229]
	v_pk_fma_f32 v[230:231], v[24:25], v[238:239], v[230:231]
	v_lshlrev_b32_e32 v232, 16, v98
	v_and_b32_e32 v233, 0xffff0000, v98
	v_lshlrev_b32_e32 v234, 16, v99
	v_and_b32_e32 v235, 0xffff0000, v99
	v_lshlrev_b32_e32 v236, 16, v100
	v_and_b32_e32 v237, 0xffff0000, v100
	v_lshlrev_b32_e32 v238, 16, v101
	v_and_b32_e32 v239, 0xffff0000, v101
	v_pk_fma_f32 v[200:201], v[26:27], v[232:233], v[200:201]
	v_pk_fma_f32 v[202:203], v[28:29], v[234:235], v[202:203]
	v_pk_fma_f32 v[204:205], v[30:31], v[236:237], v[204:205]
	v_pk_fma_f32 v[206:207], v[32:33], v[238:239], v[206:207]
	v_lshlrev_b32_e32 v232, 16, v102
	v_and_b32_e32 v233, 0xffff0000, v102
	v_lshlrev_b32_e32 v234, 16, v103
	v_and_b32_e32 v235, 0xffff0000, v103
	v_lshlrev_b32_e32 v236, 16, v104
	v_and_b32_e32 v237, 0xffff0000, v104
	v_lshlrev_b32_e32 v238, 16, v105
	v_and_b32_e32 v239, 0xffff0000, v105
	v_pk_fma_f32 v[200:201], v[34:35], v[232:233], v[200:201]
	v_pk_fma_f32 v[202:203], v[36:37], v[234:235], v[202:203]
	v_pk_fma_f32 v[204:205], v[38:39], v[236:237], v[204:205]
	v_pk_fma_f32 v[206:207], v[40:41], v[238:239], v[206:207]
	v_pk_fma_f32 v[208:209], v[26:27], v[232:233], v[208:209]
	v_pk_fma_f32 v[210:211], v[28:29], v[234:235], v[210:211]
	v_pk_fma_f32 v[212:213], v[30:31], v[236:237], v[212:213]
	v_pk_fma_f32 v[214:215], v[32:33], v[238:239], v[214:215]
	v_lshlrev_b32_e32 v232, 16, v106
	v_and_b32_e32 v233, 0xffff0000, v106
	v_lshlrev_b32_e32 v234, 16, v107
	v_and_b32_e32 v235, 0xffff0000, v107
	v_lshlrev_b32_e32 v236, 16, v108
	v_and_b32_e32 v237, 0xffff0000, v108
	v_lshlrev_b32_e32 v238, 16, v109
	v_and_b32_e32 v239, 0xffff0000, v109
	v_pk_fma_f32 v[200:201], v[42:43], v[232:233], v[200:201]
	v_pk_fma_f32 v[202:203], v[44:45], v[234:235], v[202:203]
	v_pk_fma_f32 v[204:205], v[46:47], v[236:237], v[204:205]
	v_pk_fma_f32 v[206:207], v[48:49], v[238:239], v[206:207]
	v_pk_fma_f32 v[208:209], v[34:35], v[232:233], v[208:209]
	v_pk_fma_f32 v[210:211], v[36:37], v[234:235], v[210:211]
	v_pk_fma_f32 v[212:213], v[38:39], v[236:237], v[212:213]
	v_pk_fma_f32 v[214:215], v[40:41], v[238:239], v[214:215]
	v_pk_fma_f32 v[216:217], v[26:27], v[232:233], v[216:217]
	v_pk_fma_f32 v[218:219], v[28:29], v[234:235], v[218:219]
	v_pk_fma_f32 v[220:221], v[30:31], v[236:237], v[220:221]
	v_pk_fma_f32 v[222:223], v[32:33], v[238:239], v[222:223]
	v_lshlrev_b32_e32 v232, 16, v110
	v_and_b32_e32 v233, 0xffff0000, v110
	v_lshlrev_b32_e32 v234, 16, v111
	v_and_b32_e32 v235, 0xffff0000, v111
	v_lshlrev_b32_e32 v236, 16, v112
	v_and_b32_e32 v237, 0xffff0000, v112
	v_lshlrev_b32_e32 v238, 16, v113
	v_and_b32_e32 v239, 0xffff0000, v113
	v_pk_fma_f32 v[208:209], v[42:43], v[232:233], v[208:209]
	v_pk_fma_f32 v[210:211], v[44:45], v[234:235], v[210:211]
	v_pk_fma_f32 v[212:213], v[46:47], v[236:237], v[212:213]
	v_pk_fma_f32 v[214:215], v[48:49], v[238:239], v[214:215]
	v_pk_fma_f32 v[216:217], v[34:35], v[232:233], v[216:217]
	v_pk_fma_f32 v[218:219], v[36:37], v[234:235], v[218:219]
	v_pk_fma_f32 v[220:221], v[38:39], v[236:237], v[220:221]
	v_pk_fma_f32 v[222:223], v[40:41], v[238:239], v[222:223]
	v_pk_fma_f32 v[224:225], v[26:27], v[232:233], v[224:225]
	v_pk_fma_f32 v[226:227], v[28:29], v[234:235], v[226:227]
	v_pk_fma_f32 v[228:229], v[30:31], v[236:237], v[228:229]
	v_pk_fma_f32 v[230:231], v[32:33], v[238:239], v[230:231]
	v_lshlrev_b32_e32 v232, 16, v114
	v_and_b32_e32 v233, 0xffff0000, v114
	v_lshlrev_b32_e32 v234, 16, v115
	v_and_b32_e32 v235, 0xffff0000, v115
	v_lshlrev_b32_e32 v236, 16, v116
	v_and_b32_e32 v237, 0xffff0000, v116
	v_lshlrev_b32_e32 v238, 16, v117
	v_and_b32_e32 v239, 0xffff0000, v117
	v_pk_fma_f32 v[216:217], v[42:43], v[232:233], v[216:217]
	v_pk_fma_f32 v[218:219], v[44:45], v[234:235], v[218:219]
	v_pk_fma_f32 v[220:221], v[46:47], v[236:237], v[220:221]
	v_pk_fma_f32 v[222:223], v[48:49], v[238:239], v[222:223]
	v_pk_fma_f32 v[224:225], v[34:35], v[232:233], v[224:225]
	v_pk_fma_f32 v[226:227], v[36:37], v[234:235], v[226:227]
	v_pk_fma_f32 v[228:229], v[38:39], v[236:237], v[228:229]
	v_pk_fma_f32 v[230:231], v[40:41], v[238:239], v[230:231]
	v_lshlrev_b32_e32 v232, 16, v118
	v_and_b32_e32 v233, 0xffff0000, v118
	v_lshlrev_b32_e32 v234, 16, v119
	v_and_b32_e32 v235, 0xffff0000, v119
	v_lshlrev_b32_e32 v236, 16, v120
	v_and_b32_e32 v237, 0xffff0000, v120
	v_lshlrev_b32_e32 v238, 16, v121
	v_and_b32_e32 v239, 0xffff0000, v121
	v_pk_fma_f32 v[224:225], v[42:43], v[232:233], v[224:225]
	v_pk_fma_f32 v[226:227], v[44:45], v[234:235], v[226:227]
	v_pk_fma_f32 v[228:229], v[46:47], v[236:237], v[228:229]
	v_pk_fma_f32 v[230:231], v[48:49], v[238:239], v[230:231]
	v_lshlrev_b32_e32 v232, 16, v122
	v_and_b32_e32 v233, 0xffff0000, v122
	v_lshlrev_b32_e32 v234, 16, v123
	v_and_b32_e32 v235, 0xffff0000, v123
	v_lshlrev_b32_e32 v236, 16, v124
	v_and_b32_e32 v237, 0xffff0000, v124
	v_lshlrev_b32_e32 v238, 16, v125
	v_and_b32_e32 v239, 0xffff0000, v125
	v_pk_fma_f32 v[200:201], v[50:51], v[232:233], v[200:201]
	v_pk_fma_f32 v[202:203], v[52:53], v[234:235], v[202:203]
; template <int MODE>
; __device__ __forceinline__ void conv_pass(const Params& p, int l, int gw, int nw, int lane) {
;     ...
;   for (int task = gw; task < ntask; task += nw) {
;     const uint4 c0 = nx0, c1 = nx1, c2 = nx2, c3 = nx3, c4 = nx4, c5 = nx5, c6 = nx6, c7 = nx7, c8r = nx8;
;     CONV_LOAD(task + nw)
;     int row = task >> tshift;
;     float val[8];
; #pragma unroll
;     for (int e = 0; e < 8; ++e) val[e] = 0.f;
;     CONV_TAP(c0, 0) CONV_TAP(c1, 1) CONV_TAP(c2, 2) CONV_TAP(c3, 3) CONV_TAP(c4, 4)
;     CONV_TAP(c5, 5) CONV_TAP(c6, 6) CONV_TAP(c7, 7) CONV_TAP(c8r, 8)
	v_pk_fma_f32 v[204:205], v[54:55], v[236:237], v[204:205]
	v_pk_fma_f32 v[206:207], v[56:57], v[238:239], v[206:207]
	v_lshlrev_b32_e32 v232, 16, v126
	v_and_b32_e32 v233, 0xffff0000, v126
	v_lshlrev_b32_e32 v234, 16, v127
	v_and_b32_e32 v235, 0xffff0000, v127
	v_lshlrev_b32_e32 v236, 16, v128
	v_and_b32_e32 v237, 0xffff0000, v128
	v_lshlrev_b32_e32 v238, 16, v129
	v_and_b32_e32 v239, 0xffff0000, v129
	v_pk_fma_f32 v[200:201], v[58:59], v[232:233], v[200:201]
	v_pk_fma_f32 v[202:203], v[60:61], v[234:235], v[202:203]
	v_pk_fma_f32 v[204:205], v[62:63], v[236:237], v[204:205]
	v_pk_fma_f32 v[206:207], v[64:65], v[238:239], v[206:207]
	v_pk_fma_f32 v[208:209], v[50:51], v[232:233], v[208:209]
	v_pk_fma_f32 v[210:211], v[52:53], v[234:235], v[210:211]
	v_pk_fma_f32 v[212:213], v[54:55], v[236:237], v[212:213]
	v_pk_fma_f32 v[214:215], v[56:57], v[238:239], v[214:215]
	v_lshlrev_b32_e32 v232, 16, v130
	v_and_b32_e32 v233, 0xffff0000, v130
	v_lshlrev_b32_e32 v234, 16, v131
	v_and_b32_e32 v235, 0xffff0000, v131
	v_lshlrev_b32_e32 v236, 16, v132
	v_and_b32_e32 v237, 0xffff0000, v132
	v_lshlrev_b32_e32 v238, 16, v133
	v_and_b32_e32 v239, 0xffff0000, v133
	v_pk_fma_f32 v[200:201], v[66:67], v[232:233], v[200:201]
	v_pk_fma_f32 v[202:203], v[68:69], v[234:235], v[202:203]
	v_pk_fma_f32 v[204:205], v[70:71], v[236:237], v[204:205]
	v_pk_fma_f32 v[206:207], v[72:73], v[238:239], v[206:207]
	v_pk_fma_f32 v[208:209], v[58:59], v[232:233], v[208:209]
	v_pk_fma_f32 v[210:211], v[60:61], v[234:235], v[210:211]
	v_pk_fma_f32 v[212:213], v[62:63], v[236:237], v[212:213]
	v_pk_fma_f32 v[214:215], v[64:65], v[238:239], v[214:215]
	v_pk_fma_f32 v[216:217], v[50:51], v[232:233], v[216:217]
	v_pk_fma_f32 v[218:219], v[52:53], v[234:235], v[218:219]
	v_pk_fma_f32 v[220:221], v[54:55], v[236:237], v[220:221]
	v_pk_fma_f32 v[222:223], v[56:57], v[238:239], v[222:223]
	v_lshlrev_b32_e32 v232, 16, v134
	v_and_b32_e32 v233, 0xffff0000, v134
	v_lshlrev_b32_e32 v234, 16, v135
	v_and_b32_e32 v235, 0xffff0000, v135
	v_lshlrev_b32_e32 v236, 16, v136
	v_and_b32_e32 v237, 0xffff0000, v136
	v_lshlrev_b32_e32 v238, 16, v137
	v_and_b32_e32 v239, 0xffff0000, v137
	v_pk_fma_f32 v[208:209], v[66:67], v[232:233], v[208:209]
	v_pk_fma_f32 v[210:211], v[68:69], v[234:235], v[210:211]
	v_pk_fma_f32 v[212:213], v[70:71], v[236:237], v[212:213]
	v_pk_fma_f32 v[214:215], v[72:73], v[238:239], v[214:215]
	v_pk_fma_f32 v[216:217], v[58:59], v[232:233], v[216:217]
	v_pk_fma_f32 v[218:219], v[60:61], v[234:235], v[218:219]
	v_pk_fma_f32 v[220:221], v[62:63], v[236:237], v[220:221]
	v_pk_fma_f32 v[222:223], v[64:65], v[238:239], v[222:223]
	v_pk_fma_f32 v[224:225], v[50:51], v[232:233], v[224:225]
	v_pk_fma_f32 v[226:227], v[52:53], v[234:235], v[226:227]
	v_pk_fma_f32 v[228:229], v[54:55], v[236:237], v[228:229]
	v_pk_fma_f32 v[230:231], v[56:57], v[238:239], v[230:231]
	v_lshlrev_b32_e32 v232, 16, v138
	v_and_b32_e32 v233, 0xffff0000, v138
	v_lshlrev_b32_e32 v234, 16, v139
	v_and_b32_e32 v235, 0xffff0000, v139
	v_lshlrev_b32_e32 v236, 16, v140
	v_and_b32_e32 v237, 0xffff0000, v140
	v_lshlrev_b32_e32 v238, 16, v141
	v_and_b32_e32 v239, 0xffff0000, v141
	v_pk_fma_f32 v[216:217], v[66:67], v[232:233], v[216:217]
	v_pk_fma_f32 v[218:219], v[68:69], v[234:235], v[218:219]
	v_pk_fma_f32 v[220:221], v[70:71], v[236:237], v[220:221]
	v_pk_fma_f32 v[222:223], v[72:73], v[238:239], v[222:223]
	v_pk_fma_f32 v[224:225], v[58:59], v[232:233], v[224:225]
	v_pk_fma_f32 v[226:227], v[60:61], v[234:235], v[226:227]
	v_pk_fma_f32 v[228:229], v[62:63], v[236:237], v[228:229]
	v_pk_fma_f32 v[230:231], v[64:65], v[238:239], v[230:231]
	v_lshlrev_b32_e32 v232, 16, v142
	v_and_b32_e32 v233, 0xffff0000, v142
	v_lshlrev_b32_e32 v234, 16, v143
	v_and_b32_e32 v235, 0xffff0000, v143
	v_lshlrev_b32_e32 v236, 16, v144
	v_and_b32_e32 v237, 0xffff0000, v144
	v_lshlrev_b32_e32 v238, 16, v145
	v_and_b32_e32 v239, 0xffff0000, v145
	v_pk_fma_f32 v[224:225], v[66:67], v[232:233], v[224:225]
	v_pk_fma_f32 v[226:227], v[68:69], v[234:235], v[226:227]
	v_pk_fma_f32 v[228:229], v[70:71], v[236:237], v[228:229]
	v_pk_fma_f32 v[230:231], v[72:73], v[238:239], v[230:231]
	s_add_i32 s48, s48, s49
	s_cmpk_lt_u32 s48, 0x900
	s_cbranch_scc0 .Lcv0_nonext
	s_mul_hi_u32 s10, s48, 0x71c71d
	s_mul_i32 s12, s10, 0x240
	s_sub_i32 s12, s48, s12
	s_sub_i32 s13, s12, 64
	s_and_b32 s55, s13, 15
	s_cmpk_lt_u32 s12, 64
	s_cselect_b32 s55, s12, s55
	s_cselect_b32 s10, 63, 15
	s_cselect_b32 s39, 0, 1
	s_cmp_gt_u32 s55, 0
	s_cselect_b32 s50, 4, 0
	s_cmp_lt_u32 s55, s10
	s_cselect_b32 s38, 8, 0
	s_or_b32 s50, s50, s38
	s_cmp_ge_i32 s13, 16
	s_cselect_b32 s38, 1, 0
	s_and_b32 s38, s38, s39
	s_or_b32 s50, s50, s38
	s_cmpk_lt_i32 s13, 0x1f0
	s_cselect_b32 s38, 2, 0
	s_lshl_b32 s39, s39, 1
	s_and_b32 s38, s38, s39
	s_or_b32 s50, s50, s38
	s_mul_i32 s38, s48, 0x6000
	s_add_u32 s46, s88, s38
	s_addc_u32 s47, s89, 0
	s_lshl_b32 s38, s48, 17
	s_add_u32 s52, s86, s38
	s_addc_u32 s53, s87, 0
	s_add_u32 s52, s52, 0x2800
	s_addc_u32 s53, s53, 0
	s_bitcmp1_b32 s50, 0
	s_cbranch_scc0 .Lcv0n_zr0
	s_sub_u32 s38, s46, 0x61800
	s_subb_u32 s39, s47, 0
	s_bitcmp1_b32 s50, 2
	s_cbranch_scc0 .Lcv0n_z00
	global_load_dwordx4 v[74:77], v150, s[38:39]
	s_branch .Lcv0n_d00

; __device__ __forceinline__ float siluf_(float x) { return x * __builtin_amdgcn_rcpf(1.f + __expf(-x)); }
; template <int MODE>
; __device__ __forceinline__ void conv_pass(const Params& p, int l, int gw, int nw, int lane) {
;     ...
;     float ss = 0.f;
; #pragma unroll
;     for (int e = 0; e < 8; ++e) { val[e] = siluf_(val[e]); ss += val[e] * val[e]; }
;     float scl = 1.f;
;     if (MODE == 0) {
;       ss += __shfl_xor(ss, 1); ss += __shfl_xor(ss, 2); ss += __shfl_xor(ss, 4); ss += __shfl_xor(ss, 8);
;       scl = rsqrtf(ss + 1e-6f) * (isq ? 0.08838834764831845f : 1.f);
;     }
;     uint4 o;
;     o.x = pack2(val[0] * scl, val[1] * scl); o.y = pack2(val[2] * scl, val[3] * scl);
;     o.z = pack2(val[4] * scl, val[5] * scl); o.w = pack2(val[6] * scl, val[7] * scl);
;     *(uint4*)(p.proj + (long)row * PLD + C_GQ + chn) = o;
.Lcv0n_dr2:
.Lcv0_nonext:
	v_mul_f32_e32 v244, 0xbfb8aa3b, v200
	v_mul_f32_e32 v245, 0xbfb8aa3b, v201
	v_mul_f32_e32 v246, 0xbfb8aa3b, v202
	v_mul_f32_e32 v247, 0xbfb8aa3b, v203
	v_mul_f32_e32 v248, 0xbfb8aa3b, v204
	v_mul_f32_e32 v249, 0xbfb8aa3b, v205
	v_mul_f32_e32 v250, 0xbfb8aa3b, v206
	v_mul_f32_e32 v251, 0xbfb8aa3b, v207
	v_exp_f32_e32 v244, v244
	v_exp_f32_e32 v245, v245
	v_exp_f32_e32 v246, v246
	v_exp_f32_e32 v247, v247
	v_exp_f32_e32 v248, v248
	v_exp_f32_e32 v249, v249
	v_exp_f32_e32 v250, v250
	v_exp_f32_e32 v251, v251
	v_add_f32_e32 v244, 1.0, v244
	v_add_f32_e32 v245, 1.0, v245
	v_add_f32_e32 v246, 1.0, v246
	v_add_f32_e32 v247, 1.0, v247
	v_add_f32_e32 v248, 1.0, v248
	v_add_f32_e32 v249, 1.0, v249
	v_add_f32_e32 v250, 1.0, v250
	v_add_f32_e32 v251, 1.0, v251
	v_rcp_f32_e32 v244, v244
	v_rcp_f32_e32 v245, v245
	v_rcp_f32_e32 v246, v246
	v_rcp_f32_e32 v247, v247
	v_rcp_f32_e32 v248, v248
	v_rcp_f32_e32 v249, v249
	v_rcp_f32_e32 v250, v250
	v_rcp_f32_e32 v251, v251
	v_pk_mul_f32 v[200:201], v[200:201], v[244:245]
	v_pk_mul_f32 v[202:203], v[202:203], v[246:247]
	v_pk_mul_f32 v[204:205], v[204:205], v[248:249]
	v_pk_mul_f32 v[206:207], v[206:207], v[250:251]
	v_pk_mul_f32 v[244:245], v[200:201], v[200:201]
	v_pk_mul_f32 v[246:247], v[202:203], v[202:203]
	v_pk_mul_f32 v[248:249], v[204:205], v[204:205]
	v_pk_mul_f32 v[250:251], v[206:207], v[206:207]
	v_add_f32_e32 v252, v244, v245
	v_add_f32_e32 v252, v246, v252
	v_add_f32_e32 v252, v247, v252
	v_add_f32_e32 v252, v248, v252
	v_add_f32_e32 v252, v249, v252
	v_add_f32_e32 v252, v250, v252
	v_add_f32_e32 v252, v251, v252
	s_nop 1
	v_add_f32_dpp v252, v252, v252 quad_perm:[1,0,3,2] row_mask:0xf bank_mask:0xf
	s_nop 1
	v_add_f32_dpp v252, v252, v252 quad_perm:[2,3,0,1] row_mask:0xf bank_mask:0xf
	s_nop 1
	v_add_f32_dpp v252, v252, v252 row_half_mirror row_mask:0xf bank_mask:0xf
	s_nop 1
	v_add_f32_dpp v252, v252, v252 row_mirror row_mask:0xf bank_mask:0xf
	v_add_f32_e32 v252, 0x358637bd, v252
	v_rsq_f32_e32 v252, v252
	s_nop 0
	v_mul_f32_e32 v252, v151, v252
	v_pk_mul_f32 v[200:201], v[200:201], v[252:253] op_sel_hi:[1,0]
	v_pk_mul_f32 v[202:203], v[202:203], v[252:253] op_sel_hi:[1,0]
	v_pk_mul_f32 v[204:205], v[204:205], v[252:253] op_sel_hi:[1,0]
	v_pk_mul_f32 v[206:207], v[206:207], v[252:253] op_sel_hi:[1,0]
	v_cvt_pk_bf16_f32 v188, v200, v201
	v_cvt_pk_bf16_f32 v189, v202, v203
	v_cvt_pk_bf16_f32 v190, v204, v205
	v_cvt_pk_bf16_f32 v191, v206, v207
	global_store_dwordx4 v150, v[188:191], s[44:45]
	s_add_u32 s44, s44, 0x8000
	s_addc_u32 s45, s45, 0
	v_mul_f32_e32 v244, 0xbfb8aa3b, v208
	v_mul_f32_e32 v245, 0xbfb8aa3b, v209
	v_mul_f32_e32 v246, 0xbfb8aa3b, v210
	v_mul_f32_e32 v247, 0xbfb8aa3b, v211
	v_mul_f32_e32 v248, 0xbfb8aa3b, v212
	v_mul_f32_e32 v249, 0xbfb8aa3b, v213
	v_mul_f32_e32 v250, 0xbfb8aa3b, v214
	v_mul_f32_e32 v251, 0xbfb8aa3b, v215
	v_exp_f32_e32 v244, v244
	v_exp_f32_e32 v245, v245
	v_exp_f32_e32 v246, v246
	v_exp_f32_e32 v247, v247
	v_exp_f32_e32 v248, v248
	v_exp_f32_e32 v249, v249
	v_exp_f32_e32 v250, v250
	v_exp_f32_e32 v251, v251
	v_add_f32_e32 v244, 1.0, v244
	v_add_f32_e32 v245, 1.0, v245
	v_add_f32_e32 v246, 1.0, v246
	v_add_f32_e32 v247, 1.0, v247
	v_add_f32_e32 v248, 1.0, v248
	v_add_f32_e32 v249, 1.0, v249
	v_add_f32_e32 v250, 1.0, v250
	v_add_f32_e32 v251, 1.0, v251
	v_rcp_f32_e32 v244, v244
	v_rcp_f32_e32 v245, v245
	v_rcp_f32_e32 v246, v246
	v_rcp_f32_e32 v247, v247
	v_rcp_f32_e32 v248, v248
	v_rcp_f32_e32 v249, v249
	v_rcp_f32_e32 v250, v250
	v_rcp_f32_e32 v251, v251
	v_pk_mul_f32 v[208:209], v[208:209], v[244:245]
	v_pk_mul_f32 v[210:211], v[210:211], v[246:247]
	v_pk_mul_f32 v[212:213], v[212:213], v[248:249]
	v_pk_mul_f32 v[214:215], v[214:215], v[250:251]
	v_pk_mul_f32 v[244:245], v[208:209], v[208:209]
	v_pk_mul_f32 v[246:247], v[210:211], v[210:211]
	v_pk_mul_f32 v[248:249], v[212:213], v[212:213]
	v_pk_mul_f32 v[250:251], v[214:215], v[214:215]
	v_add_f32_e32 v252, v244, v245
	v_add_f32_e32 v252, v246, v252
	v_add_f32_e32 v252, v247, v252
	v_add_f32_e32 v252, v248, v252
	v_add_f32_e32 v252, v249, v252
	v_add_f32_e32 v252, v250, v252
	v_add_f32_e32 v252, v251, v252
	s_nop 1
	v_add_f32_dpp v252, v252, v252 quad_perm:[1,0,3,2] row_mask:0xf bank_mask:0xf
	s_nop 1
	v_add_f32_dpp v252, v252, v252 quad_perm:[2,3,0,1] row_mask:0xf bank_mask:0xf
	s_nop 1
	v_add_f32_dpp v252, v252, v252 row_half_mirror row_mask:0xf bank_mask:0xf
	s_nop 1
	v_add_f32_dpp v252, v252, v252 row_mirror row_mask:0xf bank_mask:0xf
	v_add_f32_e32 v252, 0x358637bd, v252
	v_rsq_f32_e32 v252, v252
	s_nop 0
	v_mul_f32_e32 v252, v151, v252
	v_pk_mul_f32 v[208:209], v[208:209], v[252:253] op_sel_hi:[1,0]
	v_pk_mul_f32 v[210:211], v[210:211], v[252:253] op_sel_hi:[1,0]
	v_pk_mul_f32 v[212:213], v[212:213], v[252:253] op_sel_hi:[1,0]
	v_pk_mul_f32 v[214:215], v[214:215], v[252:253] op_sel_hi:[1,0]
	v_cvt_pk_bf16_f32 v188, v208, v209
	v_cvt_pk_bf16_f32 v189, v210, v211
	v_cvt_pk_bf16_f32 v190, v212, v213
	v_cvt_pk_bf16_f32 v191, v214, v215
	global_store_dwordx4 v150, v[188:191], s[44:45]
	s_add_u32 s44, s44, 0x8000
	s_addc_u32 s45, s45, 0
	v_mul_f32_e32 v244, 0xbfb8aa3b, v216
	v_mul_f32_e32 v245, 0xbfb8aa3b, v217
	v_mul_f32_e32 v246, 0xbfb8aa3b, v218
	v_mul_f32_e32 v247, 0xbfb8aa3b, v219
	v_mul_f32_e32 v248, 0xbfb8aa3b, v220
	v_mul_f32_e32 v249, 0xbfb8aa3b, v221
	v_mul_f32_e32 v250, 0xbfb8aa3b, v222
	v_mul_f32_e32 v251, 0xbfb8aa3b, v223
	v_exp_f32_e32 v244, v244
	v_exp_f32_e32 v245, v245
	v_exp_f32_e32 v246, v246
	v_exp_f32_e32 v247, v247
	v_exp_f32_e32 v248, v248
	v_exp_f32_e32 v249, v249
	v_exp_f32_e32 v250, v250
	v_exp_f32_e32 v251, v251
	v_add_f32_e32 v244, 1.0, v244
; __device__ __forceinline__ float siluf_(float x) { return x * __builtin_amdgcn_rcpf(1.f + __expf(-x)); }
; template <int MODE>
; __device__ __forceinline__ void conv_pass(const Params& p, int l, int gw, int nw, int lane) {
;     ...
;     float ss = 0.f;
; #pragma unroll
;     for (int e = 0; e < 8; ++e) { val[e] = siluf_(val[e]); ss += val[e] * val[e]; }
;     float scl = 1.f;
;     if (MODE == 0) {
;       ss += __shfl_xor(ss, 1); ss += __shfl_xor(ss, 2); ss += __shfl_xor(ss, 4); ss += __shfl_xor(ss, 8);
;       scl = rsqrtf(ss + 1e-6f) * (isq ? 0.08838834764831845f : 1.f);
;     }
;     uint4 o;
;     o.x = pack2(val[0] * scl, val[1] * scl); o.y = pack2(val[2] * scl, val[3] * scl);
;     o.z = pack2(val[4] * scl, val[5] * scl); o.w = pack2(val[6] * scl, val[7] * scl);
;     *(uint4*)(p.proj + (long)row * PLD + C_GQ + chn) = o;
;   }
	v_add_f32_e32 v245, 1.0, v245
	v_add_f32_e32 v246, 1.0, v246
	v_add_f32_e32 v247, 1.0, v247
	v_add_f32_e32 v248, 1.0, v248
	v_add_f32_e32 v249, 1.0, v249
	v_add_f32_e32 v250, 1.0, v250
	v_add_f32_e32 v251, 1.0, v251
	v_rcp_f32_e32 v244, v244
	v_rcp_f32_e32 v245, v245
	v_rcp_f32_e32 v246, v246
	v_rcp_f32_e32 v247, v247
	v_rcp_f32_e32 v248, v248
	v_rcp_f32_e32 v249, v249
	v_rcp_f32_e32 v250, v250
	v_rcp_f32_e32 v251, v251
	v_pk_mul_f32 v[216:217], v[216:217], v[244:245]
	v_pk_mul_f32 v[218:219], v[218:219], v[246:247]
	v_pk_mul_f32 v[220:221], v[220:221], v[248:249]
	v_pk_mul_f32 v[222:223], v[222:223], v[250:251]
	v_pk_mul_f32 v[244:245], v[216:217], v[216:217]
	v_pk_mul_f32 v[246:247], v[218:219], v[218:219]
	v_pk_mul_f32 v[248:249], v[220:221], v[220:221]
	v_pk_mul_f32 v[250:251], v[222:223], v[222:223]
	v_add_f32_e32 v252, v244, v245
	v_add_f32_e32 v252, v246, v252
	v_add_f32_e32 v252, v247, v252
	v_add_f32_e32 v252, v248, v252
	v_add_f32_e32 v252, v249, v252
	v_add_f32_e32 v252, v250, v252
	v_add_f32_e32 v252, v251, v252
	s_nop 1
	v_add_f32_dpp v252, v252, v252 quad_perm:[1,0,3,2] row_mask:0xf bank_mask:0xf
	s_nop 1
	v_add_f32_dpp v252, v252, v252 quad_perm:[2,3,0,1] row_mask:0xf bank_mask:0xf
	s_nop 1
	v_add_f32_dpp v252, v252, v252 row_half_mirror row_mask:0xf bank_mask:0xf
	s_nop 1
	v_add_f32_dpp v252, v252, v252 row_mirror row_mask:0xf bank_mask:0xf
	v_add_f32_e32 v252, 0x358637bd, v252
	v_rsq_f32_e32 v252, v252
	s_nop 0
	v_mul_f32_e32 v252, v151, v252
	v_pk_mul_f32 v[216:217], v[216:217], v[252:253] op_sel_hi:[1,0]
	v_pk_mul_f32 v[218:219], v[218:219], v[252:253] op_sel_hi:[1,0]
	v_pk_mul_f32 v[220:221], v[220:221], v[252:253] op_sel_hi:[1,0]
	v_pk_mul_f32 v[222:223], v[222:223], v[252:253] op_sel_hi:[1,0]
	v_cvt_pk_bf16_f32 v188, v216, v217
	v_cvt_pk_bf16_f32 v189, v218, v219
	v_cvt_pk_bf16_f32 v190, v220, v221
	v_cvt_pk_bf16_f32 v191, v222, v223
	global_store_dwordx4 v150, v[188:191], s[44:45]
	s_add_u32 s44, s44, 0x8000
	s_addc_u32 s45, s45, 0
	v_mul_f32_e32 v244, 0xbfb8aa3b, v224
	v_mul_f32_e32 v245, 0xbfb8aa3b, v225
	v_mul_f32_e32 v246, 0xbfb8aa3b, v226
	v_mul_f32_e32 v247, 0xbfb8aa3b, v227
	v_mul_f32_e32 v248, 0xbfb8aa3b, v228
	v_mul_f32_e32 v249, 0xbfb8aa3b, v229
	v_mul_f32_e32 v250, 0xbfb8aa3b, v230
	v_mul_f32_e32 v251, 0xbfb8aa3b, v231
	v_exp_f32_e32 v244, v244
	v_exp_f32_e32 v245, v245
	v_exp_f32_e32 v246, v246
	v_exp_f32_e32 v247, v247
	v_exp_f32_e32 v248, v248
	v_exp_f32_e32 v249, v249
	v_exp_f32_e32 v250, v250
	v_exp_f32_e32 v251, v251
	v_add_f32_e32 v244, 1.0, v244
	v_add_f32_e32 v245, 1.0, v245
	v_add_f32_e32 v246, 1.0, v246
	v_add_f32_e32 v247, 1.0, v247
	v_add_f32_e32 v248, 1.0, v248
	v_add_f32_e32 v249, 1.0, v249
	v_add_f32_e32 v250, 1.0, v250
	v_add_f32_e32 v251, 1.0, v251
	v_rcp_f32_e32 v244, v244
	v_rcp_f32_e32 v245, v245
	v_rcp_f32_e32 v246, v246
	v_rcp_f32_e32 v247, v247
	v_rcp_f32_e32 v248, v248
	v_rcp_f32_e32 v249, v249
	v_rcp_f32_e32 v250, v250
	v_rcp_f32_e32 v251, v251
	v_pk_mul_f32 v[224:225], v[224:225], v[244:245]
	v_pk_mul_f32 v[226:227], v[226:227], v[246:247]
	v_pk_mul_f32 v[228:229], v[228:229], v[248:249]
	v_pk_mul_f32 v[230:231], v[230:231], v[250:251]
	v_pk_mul_f32 v[244:245], v[224:225], v[224:225]
	v_pk_mul_f32 v[246:247], v[226:227], v[226:227]
	v_pk_mul_f32 v[248:249], v[228:229], v[228:229]
	v_pk_mul_f32 v[250:251], v[230:231], v[230:231]
	v_add_f32_e32 v252, v244, v245
	v_add_f32_e32 v252, v246, v252
	v_add_f32_e32 v252, v247, v252
	v_add_f32_e32 v252, v248, v252
	v_add_f32_e32 v252, v249, v252
	v_add_f32_e32 v252, v250, v252
	v_add_f32_e32 v252, v251, v252
	s_nop 1
	v_add_f32_dpp v252, v252, v252 quad_perm:[1,0,3,2] row_mask:0xf bank_mask:0xf
	s_nop 1
	v_add_f32_dpp v252, v252, v252 quad_perm:[2,3,0,1] row_mask:0xf bank_mask:0xf
	s_nop 1
	v_add_f32_dpp v252, v252, v252 row_half_mirror row_mask:0xf bank_mask:0xf
	s_nop 1
	v_add_f32_dpp v252, v252, v252 row_mirror row_mask:0xf bank_mask:0xf
	v_add_f32_e32 v252, 0x358637bd, v252
	v_rsq_f32_e32 v252, v252
	s_nop 0
	v_mul_f32_e32 v252, v151, v252
	v_pk_mul_f32 v[224:225], v[224:225], v[252:253] op_sel_hi:[1,0]
	v_pk_mul_f32 v[226:227], v[226:227], v[252:253] op_sel_hi:[1,0]
	v_pk_mul_f32 v[228:229], v[228:229], v[252:253] op_sel_hi:[1,0]
	v_pk_mul_f32 v[230:231], v[230:231], v[252:253] op_sel_hi:[1,0]
	v_cvt_pk_bf16_f32 v188, v224, v225
	v_cvt_pk_bf16_f32 v189, v226, v227
	v_cvt_pk_bf16_f32 v190, v228, v229
	v_cvt_pk_bf16_f32 v191, v230, v231
	global_store_dwordx4 v150, v[188:191], s[44:45]
	s_cmpk_lt_u32 s48, 0x900
	s_cbranch_scc1 .Lcv0_loop
; template <int MODE>
; __device__ __forceinline__ void conv_pass(const Params& p, int l, int gw, int nw, int lane) {
;     ...
;     const int hq = gw & 1, sub = lane >> 4;
;     chn = 2048 + (hq * 4 + sub) * 128 + c8 * 8; ntask = TG * 2; tshift = 1;
;   }
;   float4 wa[9], wb[9];
;   {
;     const float* cwb = p.gdn_conv + (long)l * 9 * 3072 + chn;
; #pragma unroll
;     for (int k = 0; k < 9; ++k) { wa[k] = *(const float4*)(cwb + k * 3072); wb[k] = *(const float4*)(cwb + k * 3072 + 4); }
;   }
.Lcv0_done:
	v_and_b32_e32 v0, 63, v156
	v_lshrrev_b32_e32 v146, 4, v0
	v_and_b32_e32 v0, 15, v0
	s_and_b32 s55, s51, 1
	s_lshl_b32 s55, s55, 2
	v_add_u32_e32 v146, s55, v146
	v_lshlrev_b32_e32 v146, 7, v146
	v_lshl_add_u32 v146, v0, 3, v146
	v_add_u32_e32 v146, 0x800, v146
	v_lshlrev_b32_e32 v150, 1, v146
	v_lshlrev_b32_e32 v153, 2, v146
	s_mov_b64 s[40:41], s[42:43]
	global_load_dwordx4 v[2:5], v153, s[40:41]
	global_load_dwordx4 v[6:9], v153, s[40:41] offset:16
	s_add_u32 s40, s40, 0x3000
	s_addc_u32 s41, s41, 0
	global_load_dwordx4 v[10:13], v153, s[40:41]
	global_load_dwordx4 v[14:17], v153, s[40:41] offset:16
	s_add_u32 s40, s40, 0x3000
	s_addc_u32 s41, s41, 0
	global_load_dwordx4 v[18:21], v153, s[40:41]
	global_load_dwordx4 v[22:25], v153, s[40:41] offset:16
	s_add_u32 s40, s40, 0x3000
	s_addc_u32 s41, s41, 0
	global_load_dwordx4 v[26:29], v153, s[40:41]
	global_load_dwordx4 v[30:33], v153, s[40:41] offset:16
	s_add_u32 s40, s40, 0x3000
	s_addc_u32 s41, s41, 0
	global_load_dwordx4 v[34:37], v153, s[40:41]
	global_load_dwordx4 v[38:41], v153, s[40:41] offset:16
	s_add_u32 s40, s40, 0x3000
	s_addc_u32 s41, s41, 0
	global_load_dwordx4 v[42:45], v153, s[40:41]
	global_load_dwordx4 v[46:49], v153, s[40:41] offset:16
	s_add_u32 s40, s40, 0x3000
	s_addc_u32 s41, s41, 0
	global_load_dwordx4 v[50:53], v153, s[40:41]
	global_load_dwordx4 v[54:57], v153, s[40:41] offset:16
	s_add_u32 s40, s40, 0x3000
	s_addc_u32 s41, s41, 0
	global_load_dwordx4 v[58:61], v153, s[40:41]
	global_load_dwordx4 v[62:65], v153, s[40:41] offset:16
	s_add_u32 s40, s40, 0x3000
	s_addc_u32 s41, s41, 0
	global_load_dwordx4 v[66:69], v153, s[40:41]
	global_load_dwordx4 v[70:73], v153, s[40:41] offset:16
	s_sub_i32 s48, 0x1ff, s54
	s_lshl_b32 s48, s48, 1
	s_lshr_b32 s55, s51, 1
	s_add_i32 s48, s48, s55
	s_movk_i32 s49, 0x400
	s_cmpk_lt_u32 s48, 0x900
	s_cbranch_scc0 .Lcv1_done
	s_mul_hi_u32 s10, s48, 0x71c71d
	s_mul_i32 s12, s10, 0x240
	s_sub_i32 s12, s48, s12
	s_sub_i32 s13, s12, 64
	s_and_b32 s55, s13, 15
	s_cmpk_lt_u32 s12, 64
	s_cselect_b32 s55, s12, s55
	s_cselect_b32 s10, 63, 15
	s_cselect_b32 s39, 0, 1
	s_cmp_gt_u32 s55, 0
	s_cselect_b32 s50, 4, 0
	s_cmp_lt_u32 s55, s10
	s_cselect_b32 s38, 8, 0
	s_or_b32 s50, s50, s38
	s_cmp_ge_i32 s13, 16
	s_cselect_b32 s38, 1, 0
	s_and_b32 s38, s38, s39
	s_or_b32 s50, s50, s38
	s_cmpk_lt_i32 s13, 0x1f0
	s_cselect_b32 s38, 2, 0
	s_lshl_b32 s39, s39, 1
	s_and_b32 s38, s38, s39
	s_or_b32 s50, s50, s38
	s_mul_i32 s38, s48, 0x6000
	s_add_u32 s46, s88, s38
	s_addc_u32 s47, s89, 0
	s_lshl_b32 s38, s48, 17
	s_add_u32 s52, s86, s38
	s_addc_u32 s53, s87, 0
	s_add_u32 s52, s52, 0x2800
	s_addc_u32 s53, s53, 0
	s_bitcmp1_b32 s50, 0
	s_cbranch_scc0 .Lcv1p_zr0
	s_sub_u32 s38, s46, 0x61800
	s_subb_u32 s39, s47, 0
	s_bitcmp1_b32 s50, 2
	s_cbranch_scc0 .Lcv1p_z00
	global_load_dwordx4 v[74:77], v150, s[38:39]
	s_branch .Lcv1p_d00

; __device__ __forceinline__ float siluf_(float x) { return x * __builtin_amdgcn_rcpf(1.f + __expf(-x)); }
; template <int MODE>
; __device__ __forceinline__ void conv_pass(const Params& p, int l, int gw, int nw, int lane) {
;     ...
;     float ss = 0.f;
; #pragma unroll
;     for (int e = 0; e < 8; ++e) { val[e] = siluf_(val[e]); ss += val[e] * val[e]; }
;     float scl = 1.f;
;     if (MODE == 0) {
;       ss += __shfl_xor(ss, 1); ss += __shfl_xor(ss, 2); ss += __shfl_xor(ss, 4); ss += __shfl_xor(ss, 8);
;       scl = rsqrtf(ss + 1e-6f) * (isq ? 0.08838834764831845f : 1.f);
;     }
;     uint4 o;
;     o.x = pack2(val[0] * scl, val[1] * scl); o.y = pack2(val[2] * scl, val[3] * scl);
;     o.z = pack2(val[4] * scl, val[5] * scl); o.w = pack2(val[6] * scl, val[7] * scl);
;     *(uint4*)(p.proj + (long)row * PLD + C_GQ + chn) = o;
;   }
.Lcv1n_dr2:
.Lcv1_nonext:
	v_mul_f32_e32 v244, 0xbfb8aa3b, v200
	v_mul_f32_e32 v245, 0xbfb8aa3b, v201
	v_mul_f32_e32 v246, 0xbfb8aa3b, v202
	v_mul_f32_e32 v247, 0xbfb8aa3b, v203
	v_mul_f32_e32 v248, 0xbfb8aa3b, v204
	v_mul_f32_e32 v249, 0xbfb8aa3b, v205
	v_mul_f32_e32 v250, 0xbfb8aa3b, v206
	v_mul_f32_e32 v251, 0xbfb8aa3b, v207
	v_exp_f32_e32 v244, v244
	v_exp_f32_e32 v245, v245
	v_exp_f32_e32 v246, v246
	v_exp_f32_e32 v247, v247
	v_exp_f32_e32 v248, v248
	v_exp_f32_e32 v249, v249
	v_exp_f32_e32 v250, v250
	v_exp_f32_e32 v251, v251
	v_add_f32_e32 v244, 1.0, v244
	v_add_f32_e32 v245, 1.0, v245
	v_add_f32_e32 v246, 1.0, v246
	v_add_f32_e32 v247, 1.0, v247
	v_add_f32_e32 v248, 1.0, v248
	v_add_f32_e32 v249, 1.0, v249
	v_add_f32_e32 v250, 1.0, v250
	v_add_f32_e32 v251, 1.0, v251
	v_rcp_f32_e32 v244, v244
	v_rcp_f32_e32 v245, v245
	v_rcp_f32_e32 v246, v246
	v_rcp_f32_e32 v247, v247
	v_rcp_f32_e32 v248, v248
	v_rcp_f32_e32 v249, v249
	v_rcp_f32_e32 v250, v250
	v_rcp_f32_e32 v251, v251
	v_pk_mul_f32 v[200:201], v[200:201], v[244:245]
	v_pk_mul_f32 v[202:203], v[202:203], v[246:247]
	v_pk_mul_f32 v[204:205], v[204:205], v[248:249]
	v_pk_mul_f32 v[206:207], v[206:207], v[250:251]
	v_cvt_pk_bf16_f32 v188, v200, v201
	v_cvt_pk_bf16_f32 v189, v202, v203
	v_cvt_pk_bf16_f32 v190, v204, v205
	v_cvt_pk_bf16_f32 v191, v206, v207
	global_store_dwordx4 v150, v[188:191], s[44:45]
	s_add_u32 s44, s44, 0x8000
	s_addc_u32 s45, s45, 0
	v_mul_f32_e32 v244, 0xbfb8aa3b, v208
	v_mul_f32_e32 v245, 0xbfb8aa3b, v209
	v_mul_f32_e32 v246, 0xbfb8aa3b, v210
	v_mul_f32_e32 v247, 0xbfb8aa3b, v211
	v_mul_f32_e32 v248, 0xbfb8aa3b, v212
	v_mul_f32_e32 v249, 0xbfb8aa3b, v213
	v_mul_f32_e32 v250, 0xbfb8aa3b, v214
	v_mul_f32_e32 v251, 0xbfb8aa3b, v215
	v_exp_f32_e32 v244, v244
	v_exp_f32_e32 v245, v245
	v_exp_f32_e32 v246, v246
	v_exp_f32_e32 v247, v247
	v_exp_f32_e32 v248, v248
	v_exp_f32_e32 v249, v249
	v_exp_f32_e32 v250, v250
	v_exp_f32_e32 v251, v251
	v_add_f32_e32 v244, 1.0, v244
	v_add_f32_e32 v245, 1.0, v245
	v_add_f32_e32 v246, 1.0, v246
	v_add_f32_e32 v247, 1.0, v247
	v_add_f32_e32 v248, 1.0, v248
	v_add_f32_e32 v249, 1.0, v249
	v_add_f32_e32 v250, 1.0, v250
	v_add_f32_e32 v251, 1.0, v251
	v_rcp_f32_e32 v244, v244
	v_rcp_f32_e32 v245, v245
	v_rcp_f32_e32 v246, v246
	v_rcp_f32_e32 v247, v247
	v_rcp_f32_e32 v248, v248
	v_rcp_f32_e32 v249, v249
	v_rcp_f32_e32 v250, v250
	v_rcp_f32_e32 v251, v251
	v_pk_mul_f32 v[208:209], v[208:209], v[244:245]
	v_pk_mul_f32 v[210:211], v[210:211], v[246:247]
	v_pk_mul_f32 v[212:213], v[212:213], v[248:249]
	v_pk_mul_f32 v[214:215], v[214:215], v[250:251]
	v_cvt_pk_bf16_f32 v188, v208, v209
	v_cvt_pk_bf16_f32 v189, v210, v211
	v_cvt_pk_bf16_f32 v190, v212, v213
	v_cvt_pk_bf16_f32 v191, v214, v215
	global_store_dwordx4 v150, v[188:191], s[44:45]
	s_add_u32 s44, s44, 0x8000
	s_addc_u32 s45, s45, 0
	v_mul_f32_e32 v244, 0xbfb8aa3b, v216
	v_mul_f32_e32 v245, 0xbfb8aa3b, v217
	v_mul_f32_e32 v246, 0xbfb8aa3b, v218
	v_mul_f32_e32 v247, 0xbfb8aa3b, v219
	v_mul_f32_e32 v248, 0xbfb8aa3b, v220
	v_mul_f32_e32 v249, 0xbfb8aa3b, v221
	v_mul_f32_e32 v250, 0xbfb8aa3b, v222
	v_mul_f32_e32 v251, 0xbfb8aa3b, v223
	v_exp_f32_e32 v244, v244
	v_exp_f32_e32 v245, v245
	v_exp_f32_e32 v246, v246
	v_exp_f32_e32 v247, v247
	v_exp_f32_e32 v248, v248
	v_exp_f32_e32 v249, v249
	v_exp_f32_e32 v250, v250
	v_exp_f32_e32 v251, v251
	v_add_f32_e32 v244, 1.0, v244
	v_add_f32_e32 v245, 1.0, v245
	v_add_f32_e32 v246, 1.0, v246
	v_add_f32_e32 v247, 1.0, v247
	v_add_f32_e32 v248, 1.0, v248
	v_add_f32_e32 v249, 1.0, v249
	v_add_f32_e32 v250, 1.0, v250
	v_add_f32_e32 v251, 1.0, v251
	v_rcp_f32_e32 v244, v244
	v_rcp_f32_e32 v245, v245
	v_rcp_f32_e32 v246, v246
	v_rcp_f32_e32 v247, v247
	v_rcp_f32_e32 v248, v248
	v_rcp_f32_e32 v249, v249
	v_rcp_f32_e32 v250, v250
	v_rcp_f32_e32 v251, v251
	v_pk_mul_f32 v[216:217], v[216:217], v[244:245]
	v_pk_mul_f32 v[218:219], v[218:219], v[246:247]
	v_pk_mul_f32 v[220:221], v[220:221], v[248:249]
	v_pk_mul_f32 v[222:223], v[222:223], v[250:251]
	v_cvt_pk_bf16_f32 v188, v216, v217
	v_cvt_pk_bf16_f32 v189, v218, v219
	v_cvt_pk_bf16_f32 v190, v220, v221
	v_cvt_pk_bf16_f32 v191, v222, v223
	global_store_dwordx4 v150, v[188:191], s[44:45]
	s_add_u32 s44, s44, 0x8000
	s_addc_u32 s45, s45, 0
	v_mul_f32_e32 v244, 0xbfb8aa3b, v224
	v_mul_f32_e32 v245, 0xbfb8aa3b, v225
	v_mul_f32_e32 v246, 0xbfb8aa3b, v226
	v_mul_f32_e32 v247, 0xbfb8aa3b, v227
	v_mul_f32_e32 v248, 0xbfb8aa3b, v228
	v_mul_f32_e32 v249, 0xbfb8aa3b, v229
	v_mul_f32_e32 v250, 0xbfb8aa3b, v230
	v_mul_f32_e32 v251, 0xbfb8aa3b, v231
	v_exp_f32_e32 v244, v244
	v_exp_f32_e32 v245, v245
	v_exp_f32_e32 v246, v246
	v_exp_f32_e32 v247, v247
	v_exp_f32_e32 v248, v248
	v_exp_f32_e32 v249, v249
	v_exp_f32_e32 v250, v250
	v_exp_f32_e32 v251, v251
	v_add_f32_e32 v244, 1.0, v244
	v_add_f32_e32 v245, 1.0, v245
	v_add_f32_e32 v246, 1.0, v246
	v_add_f32_e32 v247, 1.0, v247
	v_add_f32_e32 v248, 1.0, v248
	v_add_f32_e32 v249, 1.0, v249
	v_add_f32_e32 v250, 1.0, v250
	v_add_f32_e32 v251, 1.0, v251
	v_rcp_f32_e32 v244, v244
	v_rcp_f32_e32 v245, v245
	v_rcp_f32_e32 v246, v246
	v_rcp_f32_e32 v247, v247
	v_rcp_f32_e32 v248, v248
	v_rcp_f32_e32 v249, v249
	v_rcp_f32_e32 v250, v250
	v_rcp_f32_e32 v251, v251
	v_pk_mul_f32 v[224:225], v[224:225], v[244:245]
	v_pk_mul_f32 v[226:227], v[226:227], v[246:247]
	v_pk_mul_f32 v[228:229], v[228:229], v[248:249]
	v_pk_mul_f32 v[230:231], v[230:231], v[250:251]
	v_cvt_pk_bf16_f32 v188, v224, v225
	v_cvt_pk_bf16_f32 v189, v226, v227
	v_cvt_pk_bf16_f32 v190, v228, v229
	v_cvt_pk_bf16_f32 v191, v230, v231
	global_store_dwordx4 v150, v[188:191], s[44:45]
	s_cmpk_lt_u32 s48, 0x900
	s_cbranch_scc1 .Lcv1_loop
.Lcv1_done:
	s_mov_b64 s[46:47], exec
